# P5 final tile: half of the epilogue inside the last MFMA segment, short hand-written second half, alignment barrier behind the leading group's epilogue
# speedup vs baseline: 1.0004x; 1.0004x over previous
;     __device__ __forceinline__ unsigned voffA(int R, int C) const { return (unsigned)(R * lda + C) * 2u; }
;     __device__ __forceinline__ unsigned voffB(int R, int C) const { return (unsigned)(R * ldb + C) * 2u; }
;     __device__ __forceinline__ size_t hA() const { return (size_t)HALF * lda * 2; }
;     __device__ __forceinline__ size_t hB() const { return (size_t)HALF * ldb * 2; }
;     __device__ __forceinline__ const char* a(const Unit& u) const { return (const char*)A + (size_t)u.pm * 2 * hA(); }
;     __device__ __forceinline__ const char* b(const Unit& u) const { return (const char*)Bt + (size_t)u.pn * 2 * hB() + (size_t)(u.pm >> gshift) * goff; }
;     __device__ __forceinline__ unsigned voffA(int R, int C) const { return (unsigned)(R * 256 + C) * 2u; }
; #define PG8_BAR __builtin_amdgcn_s_barrier()
;     __device__ __forceinline__ void operator()(const f32x4 (&acc)[2][2][4][2], const Unit& u, int wr, int wc, int fr, int fq) const {
;     ...
;             for (int m = 0; m < 4; ++m) rsv[ai][m] = RS ? rs[row0 + ai * HALF + m * 16] : 1.0f;
;     ...
;     for (int i = 0; i < 2; ++i) { int R, C; stage_rc(tid * 16 + i * 8192, R, C); const int Rb = Epi::PERM ? ((R & ~31) + perm32(R & 31)) : R;
;         voffA[i] = g.voffA(R, C); voffB[i] = g.voffB(Rb, C); }
;     const size_t kstep = (size_t)(BK * 2);
;     const size_t hstepA = g.hA(), hstepB = g.hB();
;     const unsigned ldsw = (unsigned)wid * 1024u;
;     const int aoff = lds_byte(wr * 64 + fr, fq * 8), boff = lds_byte(wc * 32 + fr, fq * 8);
;     ...
;     Unit cur, nxt; int ui = 0;
;     if (!S.next(0, cur)) return;
;     f32x4 acc[2][2][4][2];
; #pragma unroll
;     for (int a = 0; a < 2; ++a)
; #pragma unroll
;         for (int b = 0; b < 2; ++b)
; #pragma unroll
;             for (int m = 0; m < 4; ++m)
; #pragma unroll
;                 for (int n = 0; n < 2; ++n) acc[a][b][m][n] = (f32x4){0.f, 0.f, 0.f, 0.f};
;     bf16x8 At[4][2], B0[2][2], B1[2][2];
;     const char* cA = g.a(cur); const char* cB = g.b(cur);
;     S.a_ready(cur);
;     PG8_STAGE(PG8_SB(0, 0), cB, voffB); PG8_STAGE(PG8_SB(0, 1), cB + hstepB, voffB); PG8_STAGE(PG8_SA(0, 0), cA, voffA); PG8_STAGE(PG8_SA(0, 1), cA + hstepA, voffA);
;     if (wr == 1) PG8_BAR;
;     PG8_WAIT_V(2); PG8_BAR;
;     PG8_STAGE(PG8_SB(1, 0), cB + kstep, voffB); PG8_STAGE(PG8_SA(1, 0), cA + kstep, voffA); PG8_STAGE(PG8_SB(1, 1), cB + hstepB + kstep, voffB);
.LBB0_703:
	v_readlane_b32 s0, v254, 40
	v_readlane_b32 s1, v254, 41
	s_and_b64 s[0:1], s[0:1], s[20:21]
	s_and_b64 s[0:1], s[0:1], exec
	v_readlane_b32 s0, v254, 20
	v_readlane_b32 s1, v254, 21
	s_cselect_b32 s77, s1, s69
	s_cselect_b32 s76, s0, s68
	s_lshl_b64 s[0:1], s[78:79], 12
	s_add_u32 s30, s74, s0
	s_mov_b32 s0, s70
	s_addc_u32 s31, s75, s1
	v_mbcnt_lo_u32_b32 v0, s0, 0
	v_mbcnt_hi_u32_b32 v0, s0, v0
	v_readlane_b32 s0, v254, 22
	v_readlane_b32 s1, v254, 23
	s_and_b64 vcc, exec, s[0:1]
	s_cbranch_vccnz .LBB0_723
	v_readlane_b32 s98, v254, 36
	v_readlane_b32 s99, v254, 37
	s_lshl_b64 s[100:101], s[78:79], 2
	s_add_u32 s98, s98, s100
	s_addc_u32 s99, s99, s101
	v_readlane_b32 s100, v255, 19
	s_lshl_b32 s100, s100, 8
	s_add_i32 s100, s100, s48
	v_and_or_b32 v248, v0, 15, s100
	v_mov_b32_e32 v249, 0
	v_lshl_add_u64 v[248:249], v[248:249], 2, s[98:99]
	global_load_dword v240, v[248:249], off
	global_load_dword v241, v[248:249], off offset:64
	global_load_dword v242, v[248:249], off offset:128
	global_load_dword v243, v[248:249], off offset:192
	global_load_dword v244, v[248:249], off offset:512
	global_load_dword v245, v[248:249], off offset:576
	global_load_dword v246, v[248:249], off offset:640
	global_load_dword v247, v[248:249], off offset:704
	v_mbcnt_lo_u32_b32 v250, -1, 0
	v_mbcnt_hi_u32_b32 v250, -1, v250
	v_and_b32_e32 v251, 15, v250
	v_lshrrev_b32_e32 v250, 4, v250
	v_lshlrev_b32_e32 v250, 4, v250
	v_lshl_or_b32 v250, v251, 14, v250
	v_lshl_add_u32 v1, v0, 4, s33
	v_ashrrev_i32_e32 v2, 31, v1
	v_lshrrev_b32_e32 v2, 22, v2
	v_add_u32_e32 v2, v1, v2
	v_ashrrev_i32_e32 v2, 10, v2
	v_mul_i32_i24_e32 v3, 0x400, v2
	v_sub_u32_e32 v3, v1, v3
	v_lshrrev_b32_e32 v4, 4, v3
	v_bitop3_b32 v3, v4, v3, 32 bitop3:0x6c
	v_ashrrev_i32_e32 v5, 31, v3
	v_lshrrev_b32_e32 v5, 26, v5
	v_lshlrev_b32_e32 v4, 3, v2
	v_add_u32_e32 v5, v3, v5
	v_and_b32_e32 v4, -16, v4
	v_ashrrev_i32_e32 v6, 6, v5
	v_and_b32_e32 v5, 0xc0, v5
	v_add_u32_e32 v4, v6, v4
	v_sub_u32_e32 v3, v3, v5
	v_lshlrev_b32_e32 v2, 5, v2
	v_ashrrev_i16_sdwa v3, v228, sext(v3) dst_sel:DWORD dst_unused:UNUSED_PAD src0_sel:DWORD src1_sel:BYTE_0
	v_lshlrev_b32_e32 v5, 1, v4
	v_lshrrev_b32_e32 v7, 2, v4
	v_and_b32_e32 v6, 3, v6
	s_mov_b32 s0, 0xfffe0
	v_and_b32_e32 v2, 32, v2
	v_bfe_i32 v3, v3, 0, 16
	v_and_b32_e32 v5, 24, v5
	v_and_b32_e32 v7, 4, v7
	v_and_or_b32 v6, v4, s0, v6
	v_or3_b32 v5, v6, v7, v5
	v_add_lshl_u32 v2, v2, v3, 1
	v_add_u32_e32 v1, 0x2000, v1
	v_lshl_add_u32 v128, v4, 12, v2
	v_lshl_add_u32 v192, v5, 12, v2
	v_ashrrev_i32_e32 v2, 31, v1
	v_lshrrev_b32_e32 v2, 22, v2
	v_add_u32_e32 v2, v1, v2
	v_ashrrev_i32_e32 v2, 10, v2
	v_mul_i32_i24_e32 v3, 0x400, v2
	v_sub_u32_e32 v1, v1, v3
	v_lshrrev_b32_e32 v3, 4, v1
	v_bitop3_b32 v1, v3, v1, 32 bitop3:0x6c
	v_ashrrev_i32_e32 v4, 31, v1
	v_lshrrev_b32_e32 v4, 26, v4
	v_add_u32_e32 v4, v1, v4
	v_ashrrev_i32_e32 v5, 6, v4
	v_and_b32_e32 v4, 0xffc0, v4
	v_sub_u32_e32 v1, v1, v4
	v_lshlrev_b32_e32 v3, 3, v2
	v_lshrrev_b16_e32 v4, 7, v1
	v_and_b32_e32 v3, -16, v3
	v_and_b32_e32 v4, 1, v4
	v_add_u32_e32 v3, v5, v3
	v_add_u16_e32 v1, v1, v4
	v_lshlrev_b32_e32 v2, 5, v2
	v_ashrrev_i16_sdwa v1, v228, sext(v1) dst_sel:DWORD dst_unused:UNUSED_PAD src0_sel:DWORD src1_sel:BYTE_0
	v_lshlrev_b32_e32 v4, 1, v3
	v_lshrrev_b32_e32 v6, 2, v3
	v_and_b32_e32 v5, 3, v5
	v_and_b32_e32 v2, 32, v2
	v_bfe_i32 v1, v1, 0, 16
	v_and_b32_e32 v4, 24, v4
	v_and_b32_e32 v6, 4, v6
	v_and_or_b32 v5, v3, s0, v5
	s_add_i32 s0, s33, 0
	v_readlane_b32 s20, v255, 25
	v_or3_b32 v4, v5, v6, v4
	v_add_lshl_u32 v1, v2, v1, 1
	s_add_i32 m0, s0, 0x10000
	v_readlane_b32 s21, v255, 26
	v_lshl_add_u32 v132, v4, 12, v1
	v_lshl_add_u32 v130, v3, 12, v1
	v_cmp_ne_u32_e64 s[38:39], 1, v226
	s_nop 1
	global_load_lds_dwordx4 v192, s[20:21]
	s_add_i32 m0, s0, 0x12000
	s_nop 0
	global_load_lds_dwordx4 v132, s[20:21]
	v_readlane_b32 s20, v255, 23
	s_add_i32 m0, s0, 0x14000
	v_readlane_b32 s21, v255, 24
	s_nop 4
	global_load_lds_dwordx4 v192, s[20:21]
	s_add_i32 m0, s0, 0x16000
	s_nop 0
	global_load_lds_dwordx4 v132, s[20:21]
	v_readlane_b32 s20, v255, 21
	v_readlane_b32 s21, v255, 22
	s_add_u32 s46, s30, s20
	s_addc_u32 s47, s31, s21
	s_add_i32 s1, s0, 0x2000
	s_mov_b32 m0, s0
	s_add_u32 s20, s46, 0x80000
	global_load_lds_dwordx4 v128, s[46:47]
	s_mov_b32 m0, s1
	s_addc_u32 s21, s47, 0
	s_add_i32 s34, s0, 0x4000
	global_load_lds_dwordx4 v130, s[46:47]
	s_mov_b32 m0, s34
	s_add_i32 s35, s0, 0x6000
	global_load_lds_dwordx4 v128, s[20:21]
	s_mov_b32 m0, s35
	s_nop 0
	global_load_lds_dwordx4 v130, s[20:21]
	v_readlane_b32 s98, v255, 25
	v_readlane_b32 s99, v255, 26
	s_add_u32 s98, s98, 0x80
	s_addc_u32 s99, s99, 0
	s_add_i32 m0, s0, 0x18000
	s_nop 0
	global_load_lds_dwordx4 v192, s[98:99]
	s_add_i32 m0, s0, 0x1a000
	s_nop 0
	global_load_lds_dwordx4 v132, s[98:99]
	s_add_u32 s98, s46, 0x80
	s_addc_u32 s99, s47, 0
	s_add_i32 m0, s0, 0x8000
	s_nop 0
	global_load_lds_dwordx4 v128, s[98:99]
	s_add_i32 m0, s0, 0xa000
	s_nop 0
	global_load_lds_dwordx4 v130, s[98:99]
	v_readlane_b32 s98, v255, 27
	v_readlane_b32 s99, v255, 28
	s_add_i32 m0, s0, 0x1c000
	s_nop 0
	global_load_lds_dwordx4 v192, s[98:99]
	s_add_i32 m0, s0, 0x1e000
	s_nop 0
	global_load_lds_dwordx4 v132, s[98:99]
	v_readlane_b32 s20, v254, 26
	v_readlane_b32 s21, v254, 27
	s_andn2_b64 vcc, exec, s[20:21]
	s_cbranch_vccnz .LBB0_706
	s_barrier

;     __device__ __forceinline__ void operator()(const f32x4 (&acc)[2][2][4][2], const Unit& u, int wr, int wc, int fr, int fq) const {
;     ...
;             for (int m = 0; m < 4; ++m) { const int r = row0 + ai * HALF + m * 16;
;                 bf16_t* rowp = hm ? base + ((size_t)((r >> 12) * 8 + (colt >> 7)) * 4096 + (r & 4095)) * 128 + wc * 32 + 8 * fq : base + (size_t)r * ldc + col0;
mk_p5_chk:
	s_cmp_lg_u64 s[40:41], 0
	s_cbranch_scc1 .LBB0_716
	s_lshl_b32 s98, s74, 8
	s_add_i32 s98, s98, s48
	s_lshl_b32 s98, s98, 14
	s_lshl_b32 s99, s75, 8
	s_or_b32 s99, s99, s50
	s_lshl_b32 s99, s99, 1
	s_add_u32 s98, s98, s99
	s_add_u32 s98, s76, s98
	s_addc_u32 s99, s77, 0
	s_add_u32 s100, s98, 0x200000
	s_addc_u32 s101, s99, 0
	s_add_u32 s80, s46, 0x100
	s_addc_u32 s81, s47, 0
	s_cmp_eq_u32 s89, 28
	s_cselect_b32 s28, vcc_lo, s80
	s_cselect_b32 s29, s37, s81
	s_cselect_b32 s23, s21, s88
	s_cselect_b32 s22, s86, s87
	s_add_u32 s26, s28, 0x80
	s_addc_u32 s27, s29, 0
	s_add_u32 s66, s22, 0x80
	s_addc_u32 s67, s23, 0
	s_add_u32 s90, s46, 0x80080
	s_addc_u32 s91, s47, 0
	s_add_u32 s52, s28, 0x80000
	s_addc_u32 s53, s29, 0
	s_add_u32 s56, s22, 0x80000
	s_addc_u32 s57, s23, 0
	s_add_u32 s46, s22, 0x80080
	s_addc_u32 s47, s23, 0
	s_add_i32 s92, 0, 0x10000
	v_add_u32_e32 v133, s92, v129
	s_add_i32 s93, 0, 0x14000
	ds_read_b128 v[134:137], v133
	ds_read_b128 v[138:141], v133 offset:1024
	ds_read_b128 v[142:145], v133 offset:2048
	ds_read_b128 v[146:149], v133 offset:3072
	v_add_u32_e32 v133, s93, v129
	ds_read_b128 v[150:153], v133
	ds_read_b128 v[154:157], v133 offset:1024
	ds_read_b128 v[158:161], v133 offset:2048
	ds_read_b128 v[162:165], v133 offset:3072
	s_add_i32 m0, s0, 0xc000
	ds_read_b128 v[166:169], v131
	ds_read_b128 v[170:173], v131 offset:1024
	ds_read_b128 v[174:177], v131 offset:2048
	ds_read_b128 v[178:181], v131 offset:3072
	ds_read_b128 v[182:185], v131 offset:4096
	ds_read_b128 v[186:189], v131 offset:5120
	ds_read_b128 v[202:205], v131 offset:6144
	ds_read_b128 v[206:209], v131 offset:7168
	global_load_lds_dwordx4 v128, s[90:91]
	s_add_i32 m0, s0, 0xe000
	s_nop 0
	global_load_lds_dwordx4 v130, s[90:91]
	s_waitcnt vmcnt(8)
	s_waitcnt lgkmcnt(0)
	s_barrier
	s_setprio 1
	s_waitcnt lgkmcnt(0)
	v_mfma_f32_16x16x32_bf16 v[124:127], v[134:137], v[166:169], v[124:127]
	v_mfma_f32_16x16x32_bf16 v[120:123], v[142:145], v[166:169], v[120:123]
	v_mfma_f32_16x16x32_bf16 v[108:111], v[134:137], v[174:177], v[108:111]
	v_mfma_f32_16x16x32_bf16 v[104:107], v[142:145], v[174:177], v[104:107]
	v_mfma_f32_16x16x32_bf16 v[92:95], v[134:137], v[182:185], v[92:95]
	v_mfma_f32_16x16x32_bf16 v[88:91], v[142:145], v[182:185], v[88:91]
	v_mfma_f32_16x16x32_bf16 v[76:79], v[134:137], v[202:205], v[76:79]
	v_mfma_f32_16x16x32_bf16 v[72:75], v[142:145], v[202:205], v[72:75]
	v_mfma_f32_16x16x32_bf16 v[124:127], v[138:141], v[170:173], v[124:127]
	v_mfma_f32_16x16x32_bf16 v[120:123], v[146:149], v[170:173], v[120:123]
	v_mfma_f32_16x16x32_bf16 v[108:111], v[138:141], v[178:181], v[108:111]
	v_mfma_f32_16x16x32_bf16 v[104:107], v[146:149], v[178:181], v[104:107]
	v_mfma_f32_16x16x32_bf16 v[92:95], v[138:141], v[186:189], v[92:95]
	v_mfma_f32_16x16x32_bf16 v[88:91], v[146:149], v[186:189], v[88:91]
	v_mfma_f32_16x16x32_bf16 v[76:79], v[138:141], v[206:209], v[76:79]
	v_mfma_f32_16x16x32_bf16 v[72:75], v[146:149], v[206:209], v[72:75]
	s_setprio 0
	s_setprio 1
	v_mfma_f32_16x16x32_bf16 v[116:119], v[150:153], v[166:169], v[116:119]
	v_mfma_f32_16x16x32_bf16 v[112:115], v[158:161], v[166:169], v[112:115]
	v_mfma_f32_16x16x32_bf16 v[100:103], v[150:153], v[174:177], v[100:103]
	v_mfma_f32_16x16x32_bf16 v[96:99], v[158:161], v[174:177], v[96:99]
	v_mfma_f32_16x16x32_bf16 v[84:87], v[150:153], v[182:185], v[84:87]
	v_mfma_f32_16x16x32_bf16 v[80:83], v[158:161], v[182:185], v[80:83]
	v_mfma_f32_16x16x32_bf16 v[68:71], v[150:153], v[202:205], v[68:71]
	v_mfma_f32_16x16x32_bf16 v[64:67], v[158:161], v[202:205], v[64:67]
	v_mfma_f32_16x16x32_bf16 v[116:119], v[154:157], v[170:173], v[116:119]
	v_mfma_f32_16x16x32_bf16 v[112:115], v[162:165], v[170:173], v[112:115]
	v_mfma_f32_16x16x32_bf16 v[100:103], v[154:157], v[178:181], v[100:103]
	v_mfma_f32_16x16x32_bf16 v[96:99], v[162:165], v[178:181], v[96:99]
	v_mfma_f32_16x16x32_bf16 v[84:87], v[154:157], v[186:189], v[84:87]
	v_mfma_f32_16x16x32_bf16 v[80:83], v[162:165], v[186:189], v[80:83]
	v_mfma_f32_16x16x32_bf16 v[68:71], v[154:157], v[206:209], v[68:71]
	v_mfma_f32_16x16x32_bf16 v[64:67], v[162:165], v[206:209], v[64:67]
	s_setprio 0
	s_barrier
	s_add_i32 s90, s92, s33
	s_mov_b32 m0, s90
	ds_read_b128 v[166:169], v131 offset:16384
	ds_read_b128 v[170:173], v131 offset:17408
	ds_read_b128 v[174:177], v131 offset:18432
	ds_read_b128 v[178:181], v131 offset:19456
	ds_read_b128 v[182:185], v131 offset:20480
	ds_read_b128 v[186:189], v131 offset:21504
	ds_read_b128 v[202:205], v131 offset:22528
	ds_read_b128 v[206:209], v131 offset:23552
	global_load_lds_dwordx4 v192, s[22:23]
	s_add_i32 m0, s90, 0x2000
	s_nop 0
	global_load_lds_dwordx4 v132, s[22:23]
	s_add_i32 s22, s93, s33
	s_mov_b32 m0, s22
	s_nop 0
	global_load_lds_dwordx4 v192, s[56:57]
	s_add_i32 m0, s22, 0x2000
	s_nop 0
	global_load_lds_dwordx4 v132, s[56:57]
	s_mov_b32 m0, s0
	s_nop 0
	global_load_lds_dwordx4 v128, s[28:29]
	s_mov_b32 m0, s1
	s_nop 0
	global_load_lds_dwordx4 v130, s[28:29]
	s_waitcnt vmcnt(8)
	s_waitcnt lgkmcnt(0)
	s_barrier
	s_setprio 1
	s_waitcnt lgkmcnt(0)
	v_mfma_f32_16x16x32_bf16 v[60:63], v[134:137], v[166:169], v[60:63]
	v_mfma_f32_16x16x32_bf16 v[56:59], v[142:145], v[166:169], v[56:59]
	v_mfma_f32_16x16x32_bf16 v[44:47], v[134:137], v[174:177], v[44:47]
	v_mfma_f32_16x16x32_bf16 v[40:43], v[142:145], v[174:177], v[40:43]
	v_mfma_f32_16x16x32_bf16 v[28:31], v[134:137], v[182:185], v[28:31]
	v_mfma_f32_16x16x32_bf16 v[24:27], v[142:145], v[182:185], v[24:27]
	v_mfma_f32_16x16x32_bf16 v[12:15], v[134:137], v[202:205], v[12:15]
	v_mfma_f32_16x16x32_bf16 v[8:11], v[142:145], v[202:205], v[8:11]
	v_mfma_f32_16x16x32_bf16 v[60:63], v[138:141], v[170:173], v[60:63]
	v_mfma_f32_16x16x32_bf16 v[56:59], v[146:149], v[170:173], v[56:59]
	v_mfma_f32_16x16x32_bf16 v[44:47], v[138:141], v[178:181], v[44:47]
	v_mfma_f32_16x16x32_bf16 v[40:43], v[146:149], v[178:181], v[40:43]
	v_mfma_f32_16x16x32_bf16 v[28:31], v[138:141], v[186:189], v[28:31]
	v_mfma_f32_16x16x32_bf16 v[24:27], v[146:149], v[186:189], v[24:27]
	v_mfma_f32_16x16x32_bf16 v[12:15], v[138:141], v[206:209], v[12:15]
	v_mfma_f32_16x16x32_bf16 v[8:11], v[146:149], v[206:209], v[8:11]
	s_setprio 0
	s_setprio 1
	v_mfma_f32_16x16x32_bf16 v[52:55], v[150:153], v[166:169], v[52:55]
	v_mfma_f32_16x16x32_bf16 v[48:51], v[158:161], v[166:169], v[48:51]
	v_mfma_f32_16x16x32_bf16 v[36:39], v[150:153], v[174:177], v[36:39]
	v_mfma_f32_16x16x32_bf16 v[32:35], v[158:161], v[174:177], v[32:35]
	v_mfma_f32_16x16x32_bf16 v[20:23], v[150:153], v[182:185], v[20:23]
	v_mfma_f32_16x16x32_bf16 v[16:19], v[158:161], v[182:185], v[16:19]
	v_mfma_f32_16x16x32_bf16 v[4:7], v[150:153], v[202:205], v[4:7]
	v_mfma_f32_16x16x32_bf16 v[0:3], v[158:161], v[202:205], v[0:3]
	v_mfma_f32_16x16x32_bf16 v[52:55], v[154:157], v[170:173], v[52:55]
	v_mfma_f32_16x16x32_bf16 v[48:51], v[162:165], v[170:173], v[48:51]
	v_mfma_f32_16x16x32_bf16 v[36:39], v[154:157], v[178:181], v[36:39]
	v_mfma_f32_16x16x32_bf16 v[32:35], v[162:165], v[178:181], v[32:35]
	v_mfma_f32_16x16x32_bf16 v[20:23], v[154:157], v[186:189], v[20:23]
	v_mfma_f32_16x16x32_bf16 v[16:19], v[162:165], v[186:189], v[16:19]
	v_mfma_f32_16x16x32_bf16 v[4:7], v[154:157], v[206:209], v[4:7]
	v_mfma_f32_16x16x32_bf16 v[0:3], v[162:165], v[206:209], v[0:3]
	s_setprio 0
	s_barrier
	s_add_i32 s22, 0, 0x18000
	v_add_u32_e32 v133, s22, v129
	s_add_i32 s23, 0, 0x1c000
	ds_read_b128 v[134:137], v133
	ds_read_b128 v[138:141], v133 offset:1024
	ds_read_b128 v[142:145], v133 offset:2048
	ds_read_b128 v[146:149], v133 offset:3072
	v_add_u32_e32 v133, s23, v129
	ds_read_b128 v[150:153], v133
	ds_read_b128 v[154:157], v133 offset:1024
	ds_read_b128 v[158:161], v133 offset:2048
	ds_read_b128 v[162:165], v133 offset:3072
	s_mov_b32 m0, s34
	ds_read_b128 v[166:169], v131 offset:32768
	ds_read_b128 v[170:173], v131 offset:33792
	ds_read_b128 v[174:177], v131 offset:34816
	ds_read_b128 v[178:181], v131 offset:35840
	ds_read_b128 v[182:185], v131 offset:36864
	ds_read_b128 v[186:189], v131 offset:37888
	ds_read_b128 v[202:205], v131 offset:38912
	ds_read_b128 v[206:209], v131 offset:39936
	global_load_lds_dwordx4 v128, s[52:53]
	s_mov_b32 m0, s35
	s_nop 0
	global_load_lds_dwordx4 v130, s[52:53]
	s_waitcnt vmcnt(8)
	s_waitcnt lgkmcnt(0)
	s_barrier
	s_setprio 1
	s_waitcnt lgkmcnt(0)
	v_mfma_f32_16x16x32_bf16 v[124:127], v[134:137], v[166:169], v[124:127]
	v_mfma_f32_16x16x32_bf16 v[120:123], v[142:145], v[166:169], v[120:123]
	v_mfma_f32_16x16x32_bf16 v[108:111], v[134:137], v[174:177], v[108:111]
	v_mfma_f32_16x16x32_bf16 v[104:107], v[142:145], v[174:177], v[104:107]
	v_mfma_f32_16x16x32_bf16 v[92:95], v[134:137], v[182:185], v[92:95]
	v_mfma_f32_16x16x32_bf16 v[88:91], v[142:145], v[182:185], v[88:91]
	v_mfma_f32_16x16x32_bf16 v[76:79], v[134:137], v[202:205], v[76:79]
	v_mfma_f32_16x16x32_bf16 v[72:75], v[142:145], v[202:205], v[72:75]
	v_mfma_f32_16x16x32_bf16 v[124:127], v[138:141], v[170:173], v[124:127]
	v_mfma_f32_16x16x32_bf16 v[120:123], v[146:149], v[170:173], v[120:123]
	v_mfma_f32_16x16x32_bf16 v[108:111], v[138:141], v[178:181], v[108:111]
	v_mfma_f32_16x16x32_bf16 v[104:107], v[146:149], v[178:181], v[104:107]
	v_mfma_f32_16x16x32_bf16 v[92:95], v[138:141], v[186:189], v[92:95]
	v_mfma_f32_16x16x32_bf16 v[88:91], v[146:149], v[186:189], v[88:91]
	v_mfma_f32_16x16x32_bf16 v[76:79], v[138:141], v[206:209], v[76:79]
	v_mfma_f32_16x16x32_bf16 v[72:75], v[146:149], v[206:209], v[72:75]
	s_setprio 0
	s_setprio 1
	v_mfma_f32_16x16x32_bf16 v[116:119], v[150:153], v[166:169], v[116:119]
	v_mfma_f32_16x16x32_bf16 v[112:115], v[158:161], v[166:169], v[112:115]
	v_mfma_f32_16x16x32_bf16 v[100:103], v[150:153], v[174:177], v[100:103]
	v_mfma_f32_16x16x32_bf16 v[96:99], v[158:161], v[174:177], v[96:99]
	v_mfma_f32_16x16x32_bf16 v[84:87], v[150:153], v[182:185], v[84:87]
	v_mfma_f32_16x16x32_bf16 v[80:83], v[158:161], v[182:185], v[80:83]
	v_mfma_f32_16x16x32_bf16 v[68:71], v[150:153], v[202:205], v[68:71]
	v_mfma_f32_16x16x32_bf16 v[64:67], v[158:161], v[202:205], v[64:67]
	v_mfma_f32_16x16x32_bf16 v[116:119], v[154:157], v[170:173], v[116:119]
	v_mfma_f32_16x16x32_bf16 v[112:115], v[162:165], v[170:173], v[112:115]
	v_mfma_f32_16x16x32_bf16 v[100:103], v[154:157], v[178:181], v[100:103]
	v_mfma_f32_16x16x32_bf16 v[96:99], v[162:165], v[178:181], v[96:99]
	v_mfma_f32_16x16x32_bf16 v[84:87], v[154:157], v[186:189], v[84:87]
	v_mfma_f32_16x16x32_bf16 v[80:83], v[162:165], v[186:189], v[80:83]
	v_mfma_f32_16x16x32_bf16 v[68:71], v[154:157], v[206:209], v[68:71]
	v_mfma_f32_16x16x32_bf16 v[64:67], v[162:165], v[206:209], v[64:67]
	s_setprio 0
	s_barrier
;     __device__ __forceinline__ const char* a(const Unit& u) const { return (const char*)A + (size_t)u.pm * 2 * hA(); }
;     __device__ __forceinline__ const char* b(const Unit& u) const { return (const char*)Bt + (size_t)u.pn * 2 * hB() + (size_t)(u.pm >> gshift) * goff; }
;     __device__ __forceinline__ const char* a(const Unit& u) const { return (const char*)A + (size_t)u.pm * 2 * hA(); }
;     __device__ __forceinline__ const char* b(const Unit& u) const { return (const char*)Bt + (size_t)((u.pn >> 4) * 4096 + (u.pn & 15) * 16) * 1024 * 2 + (size_t)(u.pm >> 1) * 512; }
;     __device__ __forceinline__ const char* a(const Unit&) const { return (const char*)A; }
;     __device__ __forceinline__ const char* b(const Unit& u) const { return (const char*)Bt + ((size_t)(((u.pm >> 4) * 1024 + u.pn * 256) * 16 + (u.pm & 15)) * 512) * 2; }
;     __device__ __forceinline__ void operator()(const f32x4 (&acc)[2][2][4][2], const Unit& u, int wr, int wc, int fr, int fq) const {
;     ...
;         for (int ai = 0; ai < 2; ++ai)
; #pragma unroll
;             for (int m = 0; m < 4; ++m) { const int r = row0 + ai * HALF + m * 16;
;                 bf16_t* rowp = hm ? base + ((size_t)((r >> 12) * 8 + (colt >> 7)) * 4096 + (r & 4095)) * 128 + wc * 32 + 8 * fq : base + (size_t)r * ldc + col0;
;                 float rv = sc; if (RS == 1) rv *= rsv[ai][m]; if (RS == 2) rv *= __builtin_amdgcn_rsqf(rsv[ai][m] * (1.0f / DM) + EPS);
; #pragma unroll
;                 for (int bj = 0; bj < 2; ++bj) { f32x4 v0 = acc[ai][bj][m][0] * rv, v1 = acc[ai][bj][m][1] * rv;
;                     if (CS) { v0 = v0 * cv[bj][0]; v1 = v1 * cv[bj][1]; }
;                     if (ACT == 2) {
; #pragma unroll
;                         for (int e = 0; e < 4; ++e) { float a = v0[e] > 0.f ? v0[e] : 0.f, b = v1[e] > 0.f ? v1[e] : 0.f; v0[e] = a * a; v1[e] = b * b; } }
;                     if (k8) {
;                         u32x2 w8; w8.x = pk_fp8x4(v0); w8.y = pk_fp8x4(v1);
;                         *(u32x2*)((unsigned char*)base + ((size_t)((r >> 12) * 8 + (colt >> 7) + bj) * 4096 + (r & 4095)) * 128 + wc * 32 + 8 * fq) = w8;
;                     } else {
;                     u32x4 w; w.x = cvt_pk_bf16(v0[0], v0[1]); w.y = cvt_pk_bf16(v0[2], v0[3]); w.z = cvt_pk_bf16(v1[0], v1[1]); w.w = cvt_pk_bf16(v1[2], v1[3]);
;                     *(u32x4*)(rowp + bj * bstep) = w; } } }
	s_add_i32 s22, s22, s33
	s_mov_b32 m0, s22
	ds_read_b128 v[166:169], v131 offset:49152
	ds_read_b128 v[170:173], v131 offset:50176
	ds_read_b128 v[174:177], v131 offset:51200
	ds_read_b128 v[178:181], v131 offset:52224
	ds_read_b128 v[182:185], v131 offset:53248
	ds_read_b128 v[186:189], v131 offset:54272
	ds_read_b128 v[202:205], v131 offset:55296
	ds_read_b128 v[206:209], v131 offset:56320
	global_load_lds_dwordx4 v192, s[66:67]
	s_add_i32 m0, s22, 0x2000
	s_add_i32 s22, s23, s33
	global_load_lds_dwordx4 v132, s[66:67]
	s_mov_b32 m0, s22
	s_nop 0
	global_load_lds_dwordx4 v192, s[46:47]
	s_add_i32 m0, s22, 0x2000
	s_nop 0
	global_load_lds_dwordx4 v132, s[46:47]
	s_mov_b32 m0, s54
	s_nop 0
	global_load_lds_dwordx4 v128, s[26:27]
	s_mov_b32 m0, s55
	s_nop 0
	global_load_lds_dwordx4 v130, s[26:27]
	v_fmamk_f32 v248, v240, 0x3a000000, v227
	v_rsq_f32_e32 v248, v248
	s_nop 0
	v_pk_mul_f32 v[120:121], v[120:121], v[248:249] op_sel_hi:[1,0]
	v_pk_mul_f32 v[122:123], v[122:123], v[248:249] op_sel_hi:[1,0]
	v_pk_mul_f32 v[124:125], v[124:125], v[248:249] op_sel_hi:[1,0]
	v_pk_mul_f32 v[126:127], v[126:127], v[248:249] op_sel_hi:[1,0]
	v_max_f32_e32 v120, 0, v120
	v_max_f32_e32 v121, 0, v121
	v_max_f32_e32 v122, 0, v122
	v_max_f32_e32 v123, 0, v123
	v_max_f32_e32 v124, 0, v124
	v_max_f32_e32 v125, 0, v125
	v_max_f32_e32 v126, 0, v126
	v_max_f32_e32 v127, 0, v127
	v_pk_mul_f32 v[120:121], v[120:121], v[120:121]
	v_pk_mul_f32 v[122:123], v[122:123], v[122:123]
	v_pk_mul_f32 v[124:125], v[124:125], v[124:125]
	v_pk_mul_f32 v[126:127], v[126:127], v[126:127]
	v_cvt_pk_bf16_f32 v124, v124, v125
	v_cvt_pk_bf16_f32 v125, v126, v127
	v_cvt_pk_bf16_f32 v126, v120, v121
	v_cvt_pk_bf16_f32 v127, v122, v123
	global_store_dwordx4 v250, v[124:127], s[98:99]
	v_pk_mul_f32 v[112:113], v[112:113], v[248:249] op_sel_hi:[1,0]
	v_pk_mul_f32 v[114:115], v[114:115], v[248:249] op_sel_hi:[1,0]
	v_pk_mul_f32 v[116:117], v[116:117], v[248:249] op_sel_hi:[1,0]
	v_pk_mul_f32 v[118:119], v[118:119], v[248:249] op_sel_hi:[1,0]
	v_max_f32_e32 v112, 0, v112
	v_max_f32_e32 v113, 0, v113
	v_max_f32_e32 v114, 0, v114
	v_max_f32_e32 v115, 0, v115
	v_max_f32_e32 v116, 0, v116
	v_max_f32_e32 v117, 0, v117
	v_max_f32_e32 v118, 0, v118
	v_max_f32_e32 v119, 0, v119
	v_pk_mul_f32 v[112:113], v[112:113], v[112:113]
	v_pk_mul_f32 v[114:115], v[114:115], v[114:115]
	v_pk_mul_f32 v[116:117], v[116:117], v[116:117]
	v_pk_mul_f32 v[118:119], v[118:119], v[118:119]
	v_cvt_pk_bf16_f32 v116, v116, v117
	v_cvt_pk_bf16_f32 v117, v118, v119
	v_cvt_pk_bf16_f32 v118, v112, v113
	v_cvt_pk_bf16_f32 v119, v114, v115
	global_store_dwordx4 v250, v[116:119], s[98:99] offset:256
	s_add_u32 s98, s98, 0x40000
	s_addc_u32 s99, s99, 0
	v_fmamk_f32 v248, v241, 0x3a000000, v227
	v_rsq_f32_e32 v248, v248
	s_nop 0
	v_pk_mul_f32 v[104:105], v[104:105], v[248:249] op_sel_hi:[1,0]
	v_pk_mul_f32 v[106:107], v[106:107], v[248:249] op_sel_hi:[1,0]
	v_pk_mul_f32 v[108:109], v[108:109], v[248:249] op_sel_hi:[1,0]
	v_pk_mul_f32 v[110:111], v[110:111], v[248:249] op_sel_hi:[1,0]
	v_max_f32_e32 v104, 0, v104
	v_max_f32_e32 v105, 0, v105
	v_max_f32_e32 v106, 0, v106
	v_max_f32_e32 v107, 0, v107
	v_max_f32_e32 v108, 0, v108
	v_max_f32_e32 v109, 0, v109
	v_max_f32_e32 v110, 0, v110
	v_max_f32_e32 v111, 0, v111
	v_pk_mul_f32 v[104:105], v[104:105], v[104:105]
	v_pk_mul_f32 v[106:107], v[106:107], v[106:107]
	v_pk_mul_f32 v[108:109], v[108:109], v[108:109]
	v_pk_mul_f32 v[110:111], v[110:111], v[110:111]
	v_cvt_pk_bf16_f32 v108, v108, v109
	v_cvt_pk_bf16_f32 v109, v110, v111
	v_cvt_pk_bf16_f32 v110, v104, v105
	v_cvt_pk_bf16_f32 v111, v106, v107
	global_store_dwordx4 v250, v[108:111], s[98:99]
	v_pk_mul_f32 v[96:97], v[96:97], v[248:249] op_sel_hi:[1,0]
	v_pk_mul_f32 v[98:99], v[98:99], v[248:249] op_sel_hi:[1,0]
	v_pk_mul_f32 v[100:101], v[100:101], v[248:249] op_sel_hi:[1,0]
	v_pk_mul_f32 v[102:103], v[102:103], v[248:249] op_sel_hi:[1,0]
	v_max_f32_e32 v96, 0, v96
	v_max_f32_e32 v97, 0, v97
	v_max_f32_e32 v98, 0, v98
	v_max_f32_e32 v99, 0, v99
	v_max_f32_e32 v100, 0, v100
	v_max_f32_e32 v101, 0, v101
	v_max_f32_e32 v102, 0, v102
	v_max_f32_e32 v103, 0, v103
	v_pk_mul_f32 v[96:97], v[96:97], v[96:97]
	v_pk_mul_f32 v[98:99], v[98:99], v[98:99]
	v_pk_mul_f32 v[100:101], v[100:101], v[100:101]
	v_pk_mul_f32 v[102:103], v[102:103], v[102:103]
	v_cvt_pk_bf16_f32 v100, v100, v101
	v_cvt_pk_bf16_f32 v101, v102, v103
	v_cvt_pk_bf16_f32 v102, v96, v97
	v_cvt_pk_bf16_f32 v103, v98, v99
	global_store_dwordx4 v250, v[100:103], s[98:99] offset:256
	s_add_u32 s98, s98, 0x40000
	s_addc_u32 s99, s99, 0
	s_waitcnt vmcnt(12)
	s_waitcnt lgkmcnt(0)
	s_barrier
;     __device__ __forceinline__ const char* a(const Unit& u) const { return (const char*)A + (size_t)u.pm * 2 * hA(); }
;     __device__ __forceinline__ const char* b(const Unit& u) const { return (const char*)Bt + (size_t)u.pn * 2 * hB() + (size_t)(u.pm >> gshift) * goff; }
;     __device__ __forceinline__ const char* a(const Unit& u) const { return (const char*)A + (size_t)u.pm * 2 * hA(); }
;     __device__ __forceinline__ const char* b(const Unit& u) const { return (const char*)Bt + (size_t)((u.pn >> 4) * 4096 + (u.pn & 15) * 16) * 1024 * 2 + (size_t)(u.pm >> 1) * 512; }
;     __device__ __forceinline__ const char* a(const Unit&) const { return (const char*)A; }
;     __device__ __forceinline__ const char* b(const Unit& u) const { return (const char*)Bt + ((size_t)(((u.pm >> 4) * 1024 + u.pn * 256) * 16 + (u.pm & 15)) * 512) * 2; }
;     __device__ __forceinline__ void operator()(const f32x4 (&acc)[2][2][4][2], const Unit& u, int wr, int wc, int fr, int fq) const {
;     ...
;         for (int ai = 0; ai < 2; ++ai)
; #pragma unroll
;             for (int m = 0; m < 4; ++m) { const int r = row0 + ai * HALF + m * 16;
;                 bf16_t* rowp = hm ? base + ((size_t)((r >> 12) * 8 + (colt >> 7)) * 4096 + (r & 4095)) * 128 + wc * 32 + 8 * fq : base + (size_t)r * ldc + col0;
;                 float rv = sc; if (RS == 1) rv *= rsv[ai][m]; if (RS == 2) rv *= __builtin_amdgcn_rsqf(rsv[ai][m] * (1.0f / DM) + EPS);
; #pragma unroll
;                 for (int bj = 0; bj < 2; ++bj) { f32x4 v0 = acc[ai][bj][m][0] * rv, v1 = acc[ai][bj][m][1] * rv;
;                     if (CS) { v0 = v0 * cv[bj][0]; v1 = v1 * cv[bj][1]; }
;                     if (ACT == 2) {
; #pragma unroll
;                         for (int e = 0; e < 4; ++e) { float a = v0[e] > 0.f ? v0[e] : 0.f, b = v1[e] > 0.f ? v1[e] : 0.f; v0[e] = a * a; v1[e] = b * b; } }
;                     if (k8) {
;                         u32x2 w8; w8.x = pk_fp8x4(v0); w8.y = pk_fp8x4(v1);
;                         *(u32x2*)((unsigned char*)base + ((size_t)((r >> 12) * 8 + (colt >> 7) + bj) * 4096 + (r & 4095)) * 128 + wc * 32 + 8 * fq) = w8;
;                     } else {
;                     u32x4 w; w.x = cvt_pk_bf16(v0[0], v0[1]); w.y = cvt_pk_bf16(v0[2], v0[3]); w.z = cvt_pk_bf16(v1[0], v1[1]); w.w = cvt_pk_bf16(v1[2], v1[3]);
;                     *(u32x4*)(rowp + bj * bstep) = w; } } }
	s_setprio 1
	s_waitcnt lgkmcnt(0)
	v_mfma_f32_16x16x32_bf16 v[60:63], v[134:137], v[166:169], v[60:63]
	v_fmamk_f32 v248, v242, 0x3a000000, v227
	v_rsq_f32_e32 v248, v248
	s_nop 0
	v_mfma_f32_16x16x32_bf16 v[56:59], v[142:145], v[166:169], v[56:59]
	v_pk_mul_f32 v[88:89], v[88:89], v[248:249] op_sel_hi:[1,0]
	v_pk_mul_f32 v[90:91], v[90:91], v[248:249] op_sel_hi:[1,0]
	v_pk_mul_f32 v[92:93], v[92:93], v[248:249] op_sel_hi:[1,0]
	v_mfma_f32_16x16x32_bf16 v[44:47], v[134:137], v[174:177], v[44:47]
	v_pk_mul_f32 v[94:95], v[94:95], v[248:249] op_sel_hi:[1,0]
	v_max_f32_e32 v88, 0, v88
	v_max_f32_e32 v89, 0, v89
	v_mfma_f32_16x16x32_bf16 v[40:43], v[142:145], v[174:177], v[40:43]
	v_max_f32_e32 v90, 0, v90
	v_max_f32_e32 v91, 0, v91
	v_max_f32_e32 v92, 0, v92
	v_mfma_f32_16x16x32_bf16 v[28:31], v[134:137], v[182:185], v[28:31]
	v_max_f32_e32 v93, 0, v93
	v_max_f32_e32 v94, 0, v94
	v_max_f32_e32 v95, 0, v95
	v_mfma_f32_16x16x32_bf16 v[24:27], v[142:145], v[182:185], v[24:27]
	v_pk_mul_f32 v[88:89], v[88:89], v[88:89]
	v_pk_mul_f32 v[90:91], v[90:91], v[90:91]
	v_pk_mul_f32 v[92:93], v[92:93], v[92:93]
	v_mfma_f32_16x16x32_bf16 v[12:15], v[134:137], v[202:205], v[12:15]
	v_pk_mul_f32 v[94:95], v[94:95], v[94:95]
	v_cvt_pk_bf16_f32 v92, v92, v93
	v_cvt_pk_bf16_f32 v93, v94, v95
	v_mfma_f32_16x16x32_bf16 v[8:11], v[142:145], v[202:205], v[8:11]
	v_cvt_pk_bf16_f32 v94, v88, v89
	v_cvt_pk_bf16_f32 v95, v90, v91
	global_store_dwordx4 v250, v[92:95], s[98:99]
	v_mfma_f32_16x16x32_bf16 v[60:63], v[138:141], v[170:173], v[60:63]
	v_pk_mul_f32 v[80:81], v[80:81], v[248:249] op_sel_hi:[1,0]
	v_pk_mul_f32 v[82:83], v[82:83], v[248:249] op_sel_hi:[1,0]
	v_pk_mul_f32 v[84:85], v[84:85], v[248:249] op_sel_hi:[1,0]
	v_mfma_f32_16x16x32_bf16 v[56:59], v[146:149], v[170:173], v[56:59]
	v_pk_mul_f32 v[86:87], v[86:87], v[248:249] op_sel_hi:[1,0]
	v_max_f32_e32 v80, 0, v80
	v_max_f32_e32 v81, 0, v81
	v_mfma_f32_16x16x32_bf16 v[44:47], v[138:141], v[178:181], v[44:47]
	v_max_f32_e32 v82, 0, v82
	v_max_f32_e32 v83, 0, v83
	v_max_f32_e32 v84, 0, v84
	v_mfma_f32_16x16x32_bf16 v[40:43], v[146:149], v[178:181], v[40:43]
	v_max_f32_e32 v85, 0, v85
	v_max_f32_e32 v86, 0, v86
	v_max_f32_e32 v87, 0, v87
	v_mfma_f32_16x16x32_bf16 v[28:31], v[138:141], v[186:189], v[28:31]
	v_pk_mul_f32 v[80:81], v[80:81], v[80:81]
	v_pk_mul_f32 v[82:83], v[82:83], v[82:83]
	v_pk_mul_f32 v[84:85], v[84:85], v[84:85]
	v_mfma_f32_16x16x32_bf16 v[24:27], v[146:149], v[186:189], v[24:27]
	v_pk_mul_f32 v[86:87], v[86:87], v[86:87]
	v_cvt_pk_bf16_f32 v84, v84, v85
	v_cvt_pk_bf16_f32 v85, v86, v87
	v_mfma_f32_16x16x32_bf16 v[12:15], v[138:141], v[206:209], v[12:15]
	v_cvt_pk_bf16_f32 v86, v80, v81
	v_cvt_pk_bf16_f32 v87, v82, v83
	global_store_dwordx4 v250, v[84:87], s[98:99] offset:256
	v_mfma_f32_16x16x32_bf16 v[8:11], v[146:149], v[206:209], v[8:11]
	s_add_u32 s98, s98, 0x40000
	s_addc_u32 s99, s99, 0
	v_fmamk_f32 v248, v243, 0x3a000000, v227
	s_setprio 0
	s_setprio 1
	v_mfma_f32_16x16x32_bf16 v[52:55], v[150:153], v[166:169], v[52:55]
	v_rsq_f32_e32 v248, v248
	s_nop 0
	v_pk_mul_f32 v[72:73], v[72:73], v[248:249] op_sel_hi:[1,0]
	v_mfma_f32_16x16x32_bf16 v[48:51], v[158:161], v[166:169], v[48:51]
	v_pk_mul_f32 v[74:75], v[74:75], v[248:249] op_sel_hi:[1,0]
	v_pk_mul_f32 v[76:77], v[76:77], v[248:249] op_sel_hi:[1,0]
	v_pk_mul_f32 v[78:79], v[78:79], v[248:249] op_sel_hi:[1,0]
	v_mfma_f32_16x16x32_bf16 v[36:39], v[150:153], v[174:177], v[36:39]
	v_max_f32_e32 v72, 0, v72
	v_max_f32_e32 v73, 0, v73
	v_max_f32_e32 v74, 0, v74
	v_mfma_f32_16x16x32_bf16 v[32:35], v[158:161], v[174:177], v[32:35]
	v_max_f32_e32 v75, 0, v75
	v_max_f32_e32 v76, 0, v76
	v_max_f32_e32 v77, 0, v77
	v_mfma_f32_16x16x32_bf16 v[20:23], v[150:153], v[182:185], v[20:23]
	v_max_f32_e32 v78, 0, v78
	v_max_f32_e32 v79, 0, v79
	v_pk_mul_f32 v[72:73], v[72:73], v[72:73]
	v_mfma_f32_16x16x32_bf16 v[16:19], v[158:161], v[182:185], v[16:19]
	v_pk_mul_f32 v[74:75], v[74:75], v[74:75]
	v_pk_mul_f32 v[76:77], v[76:77], v[76:77]
	v_pk_mul_f32 v[78:79], v[78:79], v[78:79]
	v_mfma_f32_16x16x32_bf16 v[4:7], v[150:153], v[202:205], v[4:7]
	v_cvt_pk_bf16_f32 v76, v76, v77
	v_cvt_pk_bf16_f32 v77, v78, v79
	v_cvt_pk_bf16_f32 v78, v72, v73
	v_mfma_f32_16x16x32_bf16 v[0:3], v[158:161], v[202:205], v[0:3]
	v_cvt_pk_bf16_f32 v79, v74, v75
	global_store_dwordx4 v250, v[76:79], s[98:99]
	v_pk_mul_f32 v[64:65], v[64:65], v[248:249] op_sel_hi:[1,0]
	v_mfma_f32_16x16x32_bf16 v[52:55], v[154:157], v[170:173], v[52:55]
	v_pk_mul_f32 v[66:67], v[66:67], v[248:249] op_sel_hi:[1,0]
	v_pk_mul_f32 v[68:69], v[68:69], v[248:249] op_sel_hi:[1,0]
	v_pk_mul_f32 v[70:71], v[70:71], v[248:249] op_sel_hi:[1,0]
	v_mfma_f32_16x16x32_bf16 v[48:51], v[162:165], v[170:173], v[48:51]
	v_max_f32_e32 v64, 0, v64
	v_max_f32_e32 v65, 0, v65
	v_max_f32_e32 v66, 0, v66
	v_mfma_f32_16x16x32_bf16 v[36:39], v[154:157], v[178:181], v[36:39]
	v_max_f32_e32 v67, 0, v67
	v_max_f32_e32 v68, 0, v68
	v_max_f32_e32 v69, 0, v69
	v_mfma_f32_16x16x32_bf16 v[32:35], v[162:165], v[178:181], v[32:35]
	v_max_f32_e32 v70, 0, v70
	v_max_f32_e32 v71, 0, v71
	v_pk_mul_f32 v[64:65], v[64:65], v[64:65]
	v_mfma_f32_16x16x32_bf16 v[20:23], v[154:157], v[186:189], v[20:23]
	v_pk_mul_f32 v[66:67], v[66:67], v[66:67]
	v_pk_mul_f32 v[68:69], v[68:69], v[68:69]
	v_pk_mul_f32 v[70:71], v[70:71], v[70:71]
	v_mfma_f32_16x16x32_bf16 v[16:19], v[162:165], v[186:189], v[16:19]
	v_cvt_pk_bf16_f32 v68, v68, v69
	v_cvt_pk_bf16_f32 v69, v70, v71
	v_cvt_pk_bf16_f32 v70, v64, v65
	v_mfma_f32_16x16x32_bf16 v[4:7], v[154:157], v[206:209], v[4:7]
	v_cvt_pk_bf16_f32 v71, v66, v67
	global_store_dwordx4 v250, v[68:71], s[98:99] offset:256
	s_add_u32 s98, s98, 0x40000
	v_mfma_f32_16x16x32_bf16 v[0:3], v[162:165], v[206:209], v[0:3]
	s_addc_u32 s99, s99, 0
	s_setprio 0
	s_barrier
;     __device__ __forceinline__ const char* a(const Unit& u) const { return (const char*)A + (size_t)u.pm * 2 * hA(); }
;     __device__ __forceinline__ const char* b(const Unit& u) const { return (const char*)Bt + (size_t)u.pn * 2 * hB() + (size_t)(u.pm >> gshift) * goff; }
;     __device__ __forceinline__ const char* a(const Unit& u) const { return (const char*)A + (size_t)u.pm * 2 * hA(); }
;     __device__ __forceinline__ const char* b(const Unit& u) const { return (const char*)Bt + (size_t)((u.pn >> 4) * 4096 + (u.pn & 15) * 16) * 1024 * 2 + (size_t)(u.pm >> 1) * 512; }
;     __device__ __forceinline__ const char* a(const Unit&) const { return (const char*)A; }
;     __device__ __forceinline__ const char* b(const Unit& u) const { return (const char*)Bt + ((size_t)(((u.pm >> 4) * 1024 + u.pn * 256) * 16 + (u.pm & 15)) * 512) * 2; }
;     __device__ __forceinline__ void operator()(const f32x4 (&acc)[2][2][4][2], const Unit& u, int wr, int wc, int fr, int fq) const {
;     ...
;         for (int ai = 0; ai < 2; ++ai)
; #pragma unroll
;             for (int m = 0; m < 4; ++m) { const int r = row0 + ai * HALF + m * 16;
;                 bf16_t* rowp = hm ? base + ((size_t)((r >> 12) * 8 + (colt >> 7)) * 4096 + (r & 4095)) * 128 + wc * 32 + 8 * fq : base + (size_t)r * ldc + col0;
;                 float rv = sc; if (RS == 1) rv *= rsv[ai][m]; if (RS == 2) rv *= __builtin_amdgcn_rsqf(rsv[ai][m] * (1.0f / DM) + EPS);
; #pragma unroll
;                 for (int bj = 0; bj < 2; ++bj) { f32x4 v0 = acc[ai][bj][m][0] * rv, v1 = acc[ai][bj][m][1] * rv;
;                     if (CS) { v0 = v0 * cv[bj][0]; v1 = v1 * cv[bj][1]; }
;                     if (ACT == 2) {
; #pragma unroll
;                         for (int e = 0; e < 4; ++e) { float a = v0[e] > 0.f ? v0[e] : 0.f, b = v1[e] > 0.f ? v1[e] : 0.f; v0[e] = a * a; v1[e] = b * b; } }
;                     if (k8) {
;                         u32x2 w8; w8.x = pk_fp8x4(v0); w8.y = pk_fp8x4(v1);
;                         *(u32x2*)((unsigned char*)base + ((size_t)((r >> 12) * 8 + (colt >> 7) + bj) * 4096 + (r & 4095)) * 128 + wc * 32 + 8 * fq) = w8;
;                     } else {
;                     u32x4 w; w.x = cvt_pk_bf16(v0[0], v0[1]); w.y = cvt_pk_bf16(v0[2], v0[3]); w.z = cvt_pk_bf16(v1[0], v1[1]); w.w = cvt_pk_bf16(v1[2], v1[3]);
;                     *(u32x4*)(rowp + bj * bstep) = w; } } }
	s_nop 7
	v_fmamk_f32 v248, v244, 0x3a000000, v227
	v_rsq_f32_e32 v248, v248
	s_nop 0
	v_pk_mul_f32 v[56:57], v[56:57], v[248:249] op_sel_hi:[1,0]
	v_pk_mul_f32 v[58:59], v[58:59], v[248:249] op_sel_hi:[1,0]
	v_pk_mul_f32 v[60:61], v[60:61], v[248:249] op_sel_hi:[1,0]
	v_pk_mul_f32 v[62:63], v[62:63], v[248:249] op_sel_hi:[1,0]
	v_max_f32_e32 v56, 0, v56
	v_max_f32_e32 v57, 0, v57
	v_max_f32_e32 v58, 0, v58
	v_max_f32_e32 v59, 0, v59
	v_max_f32_e32 v60, 0, v60
	v_max_f32_e32 v61, 0, v61
	v_max_f32_e32 v62, 0, v62
	v_max_f32_e32 v63, 0, v63
	v_pk_mul_f32 v[56:57], v[56:57], v[56:57]
	v_pk_mul_f32 v[58:59], v[58:59], v[58:59]
	v_pk_mul_f32 v[60:61], v[60:61], v[60:61]
	v_pk_mul_f32 v[62:63], v[62:63], v[62:63]
	v_cvt_pk_bf16_f32 v60, v60, v61
	v_cvt_pk_bf16_f32 v61, v62, v63
	v_cvt_pk_bf16_f32 v62, v56, v57
	v_cvt_pk_bf16_f32 v63, v58, v59
	global_store_dwordx4 v250, v[60:63], s[100:101]
	v_pk_mul_f32 v[48:49], v[48:49], v[248:249] op_sel_hi:[1,0]
	v_pk_mul_f32 v[50:51], v[50:51], v[248:249] op_sel_hi:[1,0]
	v_pk_mul_f32 v[52:53], v[52:53], v[248:249] op_sel_hi:[1,0]
	v_pk_mul_f32 v[54:55], v[54:55], v[248:249] op_sel_hi:[1,0]
	v_max_f32_e32 v48, 0, v48
	v_max_f32_e32 v49, 0, v49
	v_max_f32_e32 v50, 0, v50
	v_max_f32_e32 v51, 0, v51
	v_max_f32_e32 v52, 0, v52
	v_max_f32_e32 v53, 0, v53
	v_max_f32_e32 v54, 0, v54
	v_max_f32_e32 v55, 0, v55
	v_pk_mul_f32 v[48:49], v[48:49], v[48:49]
	v_pk_mul_f32 v[50:51], v[50:51], v[50:51]
	v_pk_mul_f32 v[52:53], v[52:53], v[52:53]
	v_pk_mul_f32 v[54:55], v[54:55], v[54:55]
	v_cvt_pk_bf16_f32 v52, v52, v53
	v_cvt_pk_bf16_f32 v53, v54, v55
	v_cvt_pk_bf16_f32 v54, v48, v49
	v_cvt_pk_bf16_f32 v55, v50, v51
	global_store_dwordx4 v250, v[52:55], s[100:101] offset:256
	s_add_u32 s100, s100, 0x40000
	s_addc_u32 s101, s101, 0
	v_fmamk_f32 v248, v245, 0x3a000000, v227
	v_rsq_f32_e32 v248, v248
	s_nop 0
	v_pk_mul_f32 v[40:41], v[40:41], v[248:249] op_sel_hi:[1,0]
	v_pk_mul_f32 v[42:43], v[42:43], v[248:249] op_sel_hi:[1,0]
	v_pk_mul_f32 v[44:45], v[44:45], v[248:249] op_sel_hi:[1,0]
	v_pk_mul_f32 v[46:47], v[46:47], v[248:249] op_sel_hi:[1,0]
	v_max_f32_e32 v40, 0, v40
	v_max_f32_e32 v41, 0, v41
	v_max_f32_e32 v42, 0, v42
	v_max_f32_e32 v43, 0, v43
	v_max_f32_e32 v44, 0, v44
	v_max_f32_e32 v45, 0, v45
	v_max_f32_e32 v46, 0, v46
	v_max_f32_e32 v47, 0, v47
	v_pk_mul_f32 v[40:41], v[40:41], v[40:41]
	v_pk_mul_f32 v[42:43], v[42:43], v[42:43]
	v_pk_mul_f32 v[44:45], v[44:45], v[44:45]
	v_pk_mul_f32 v[46:47], v[46:47], v[46:47]
	v_cvt_pk_bf16_f32 v44, v44, v45
	v_cvt_pk_bf16_f32 v45, v46, v47
	v_cvt_pk_bf16_f32 v46, v40, v41
	v_cvt_pk_bf16_f32 v47, v42, v43
	global_store_dwordx4 v250, v[44:47], s[100:101]
	v_pk_mul_f32 v[32:33], v[32:33], v[248:249] op_sel_hi:[1,0]
	v_pk_mul_f32 v[34:35], v[34:35], v[248:249] op_sel_hi:[1,0]
	v_pk_mul_f32 v[36:37], v[36:37], v[248:249] op_sel_hi:[1,0]
	v_pk_mul_f32 v[38:39], v[38:39], v[248:249] op_sel_hi:[1,0]
	v_max_f32_e32 v32, 0, v32
	v_max_f32_e32 v33, 0, v33
	v_max_f32_e32 v34, 0, v34
	v_max_f32_e32 v35, 0, v35
	v_max_f32_e32 v36, 0, v36
	v_max_f32_e32 v37, 0, v37
	v_max_f32_e32 v38, 0, v38
	v_max_f32_e32 v39, 0, v39
	v_pk_mul_f32 v[32:33], v[32:33], v[32:33]
	v_pk_mul_f32 v[34:35], v[34:35], v[34:35]
	v_pk_mul_f32 v[36:37], v[36:37], v[36:37]
	v_pk_mul_f32 v[38:39], v[38:39], v[38:39]
	v_cvt_pk_bf16_f32 v36, v36, v37
	v_cvt_pk_bf16_f32 v37, v38, v39
	v_cvt_pk_bf16_f32 v38, v32, v33
	v_cvt_pk_bf16_f32 v39, v34, v35
	global_store_dwordx4 v250, v[36:39], s[100:101] offset:256
	s_add_u32 s100, s100, 0x40000
	s_addc_u32 s101, s101, 0
;     __device__ __forceinline__ const char* a(const Unit& u) const { return (const char*)A + (size_t)u.pm * 2 * hA(); }
;     __device__ __forceinline__ const char* b(const Unit& u) const { return (const char*)Bt + (size_t)u.pn * 2 * hB() + (size_t)(u.pm >> gshift) * goff; }
; #define PG8_BAR __builtin_amdgcn_s_barrier()
;     __device__ __forceinline__ void operator()(const f32x4 (&acc)[2][2][4][2], const Unit& u, int wr, int wc, int fr, int fq) const {
;     ...
;         for (int ai = 0; ai < 2; ++ai)
; #pragma unroll
;             for (int m = 0; m < 4; ++m) { const int r = row0 + ai * HALF + m * 16;
;                 bf16_t* rowp = hm ? base + ((size_t)((r >> 12) * 8 + (colt >> 7)) * 4096 + (r & 4095)) * 128 + wc * 32 + 8 * fq : base + (size_t)r * ldc + col0;
;                 float rv = sc; if (RS == 1) rv *= rsv[ai][m]; if (RS == 2) rv *= __builtin_amdgcn_rsqf(rsv[ai][m] * (1.0f / DM) + EPS);
; #pragma unroll
;                 for (int bj = 0; bj < 2; ++bj) { f32x4 v0 = acc[ai][bj][m][0] * rv, v1 = acc[ai][bj][m][1] * rv;
;                     if (CS) { v0 = v0 * cv[bj][0]; v1 = v1 * cv[bj][1]; }
;                     if (ACT == 2) {
; #pragma unroll
;                         for (int e = 0; e < 4; ++e) { float a = v0[e] > 0.f ? v0[e] : 0.f, b = v1[e] > 0.f ? v1[e] : 0.f; v0[e] = a * a; v1[e] = b * b; } }
;                     if (k8) {
;                         u32x2 w8; w8.x = pk_fp8x4(v0); w8.y = pk_fp8x4(v1);
;                         *(u32x2*)((unsigned char*)base + ((size_t)((r >> 12) * 8 + (colt >> 7) + bj) * 4096 + (r & 4095)) * 128 + wc * 32 + 8 * fq) = w8;
;                     } else {
;                     u32x4 w; w.x = cvt_pk_bf16(v0[0], v0[1]); w.y = cvt_pk_bf16(v0[2], v0[3]); w.z = cvt_pk_bf16(v1[0], v1[1]); w.w = cvt_pk_bf16(v1[2], v1[3]);
;                     *(u32x4*)(rowp + bj * bstep) = w; } } }
;     ...
;         if constexpr (ALIGN_EPI) { if (wr == 0) PG8_BAR; }
;         E(acc, cur, wr, wc, 0, 0); S.done(cur);
;         if (!has_next) break;
; #pragma unroll
;         for (int a = 0; a < 2; ++a)
; #pragma unroll
;             for (int b = 0; b < 2; ++b)
; #pragma unroll
;                 for (int m = 0; m < 4; ++m)
; #pragma unroll
;                     for (int n = 0; n < 2; ++n) acc[a][b][m][n] = (f32x4){0.f, 0.f, 0.f, 0.f};
;         cur = nxt; cA = nA; cB = nB; ++ui;
;         if constexpr (ALIGN_EPI) { if (wr == 1) PG8_BAR; }
	v_fmamk_f32 v248, v246, 0x3a000000, v227
	v_rsq_f32_e32 v248, v248
	s_nop 0
	v_pk_mul_f32 v[24:25], v[24:25], v[248:249] op_sel_hi:[1,0]
	v_pk_mul_f32 v[26:27], v[26:27], v[248:249] op_sel_hi:[1,0]
	v_pk_mul_f32 v[28:29], v[28:29], v[248:249] op_sel_hi:[1,0]
	v_pk_mul_f32 v[30:31], v[30:31], v[248:249] op_sel_hi:[1,0]
	v_max_f32_e32 v24, 0, v24
	v_max_f32_e32 v25, 0, v25
	v_max_f32_e32 v26, 0, v26
	v_max_f32_e32 v27, 0, v27
	v_max_f32_e32 v28, 0, v28
	v_max_f32_e32 v29, 0, v29
	v_max_f32_e32 v30, 0, v30
	v_max_f32_e32 v31, 0, v31
	v_pk_mul_f32 v[24:25], v[24:25], v[24:25]
	v_pk_mul_f32 v[26:27], v[26:27], v[26:27]
	v_pk_mul_f32 v[28:29], v[28:29], v[28:29]
	v_pk_mul_f32 v[30:31], v[30:31], v[30:31]
	v_cvt_pk_bf16_f32 v28, v28, v29
	v_cvt_pk_bf16_f32 v29, v30, v31
	v_cvt_pk_bf16_f32 v30, v24, v25
	v_cvt_pk_bf16_f32 v31, v26, v27
	global_store_dwordx4 v250, v[28:31], s[100:101]
	v_pk_mul_f32 v[16:17], v[16:17], v[248:249] op_sel_hi:[1,0]
	v_pk_mul_f32 v[18:19], v[18:19], v[248:249] op_sel_hi:[1,0]
	v_pk_mul_f32 v[20:21], v[20:21], v[248:249] op_sel_hi:[1,0]
	v_pk_mul_f32 v[22:23], v[22:23], v[248:249] op_sel_hi:[1,0]
	v_max_f32_e32 v16, 0, v16
	v_max_f32_e32 v17, 0, v17
	v_max_f32_e32 v18, 0, v18
	v_max_f32_e32 v19, 0, v19
	v_max_f32_e32 v20, 0, v20
	v_max_f32_e32 v21, 0, v21
	v_max_f32_e32 v22, 0, v22
	v_max_f32_e32 v23, 0, v23
	v_pk_mul_f32 v[16:17], v[16:17], v[16:17]
	v_pk_mul_f32 v[18:19], v[18:19], v[18:19]
	v_pk_mul_f32 v[20:21], v[20:21], v[20:21]
	v_pk_mul_f32 v[22:23], v[22:23], v[22:23]
	v_cvt_pk_bf16_f32 v20, v20, v21
	v_cvt_pk_bf16_f32 v21, v22, v23
	v_cvt_pk_bf16_f32 v22, v16, v17
	v_cvt_pk_bf16_f32 v23, v18, v19
	global_store_dwordx4 v250, v[20:23], s[100:101] offset:256
	s_add_u32 s100, s100, 0x40000
	s_addc_u32 s101, s101, 0
	v_fmamk_f32 v248, v247, 0x3a000000, v227
	v_rsq_f32_e32 v248, v248
	s_nop 0
	v_pk_mul_f32 v[8:9], v[8:9], v[248:249] op_sel_hi:[1,0]
	v_pk_mul_f32 v[10:11], v[10:11], v[248:249] op_sel_hi:[1,0]
	v_pk_mul_f32 v[12:13], v[12:13], v[248:249] op_sel_hi:[1,0]
	v_pk_mul_f32 v[14:15], v[14:15], v[248:249] op_sel_hi:[1,0]
	v_max_f32_e32 v8, 0, v8
	v_max_f32_e32 v9, 0, v9
	v_max_f32_e32 v10, 0, v10
	v_max_f32_e32 v11, 0, v11
	v_max_f32_e32 v12, 0, v12
	v_max_f32_e32 v13, 0, v13
	v_max_f32_e32 v14, 0, v14
	v_max_f32_e32 v15, 0, v15
	v_pk_mul_f32 v[8:9], v[8:9], v[8:9]
	v_pk_mul_f32 v[10:11], v[10:11], v[10:11]
	v_pk_mul_f32 v[12:13], v[12:13], v[12:13]
	v_pk_mul_f32 v[14:15], v[14:15], v[14:15]
	v_cvt_pk_bf16_f32 v12, v12, v13
	v_cvt_pk_bf16_f32 v13, v14, v15
	v_cvt_pk_bf16_f32 v14, v8, v9
	v_cvt_pk_bf16_f32 v15, v10, v11
	global_store_dwordx4 v250, v[12:15], s[100:101]
	v_pk_mul_f32 v[0:1], v[0:1], v[248:249] op_sel_hi:[1,0]
	v_pk_mul_f32 v[2:3], v[2:3], v[248:249] op_sel_hi:[1,0]
	v_pk_mul_f32 v[4:5], v[4:5], v[248:249] op_sel_hi:[1,0]
	v_pk_mul_f32 v[6:7], v[6:7], v[248:249] op_sel_hi:[1,0]
	v_max_f32_e32 v0, 0, v0
	v_max_f32_e32 v1, 0, v1
	v_max_f32_e32 v2, 0, v2
	v_max_f32_e32 v3, 0, v3
	v_max_f32_e32 v4, 0, v4
	v_max_f32_e32 v5, 0, v5
	v_max_f32_e32 v6, 0, v6
	v_max_f32_e32 v7, 0, v7
	v_pk_mul_f32 v[0:1], v[0:1], v[0:1]
	v_pk_mul_f32 v[2:3], v[2:3], v[2:3]
	v_pk_mul_f32 v[4:5], v[4:5], v[4:5]
	v_pk_mul_f32 v[6:7], v[6:7], v[6:7]
	v_cvt_pk_bf16_f32 v4, v4, v5
	v_cvt_pk_bf16_f32 v5, v6, v7
	v_cvt_pk_bf16_f32 v6, v0, v1
	v_cvt_pk_bf16_f32 v7, v2, v3
	global_store_dwordx4 v250, v[4:7], s[100:101] offset:256
	s_add_u32 s100, s100, 0x40000
	s_addc_u32 s101, s101, 0
	s_cmp_lg_u64 s[82:83], 0
	s_cbranch_scc0 mk_p5_fin_nobar
	s_barrier
mk_p5_fin_nobar:
	s_mov_b64 s[22:23], -1
	s_branch .LBB0_708
